# v20 plus nt hint on the norm phase's fold-path partial/xc loads and on the attention q loads
# baseline (speedup 1.0000x reference)
.LBB0_450:
	s_lshl_b32 s7, s11, 1
	s_bfe_u32 s23, s11, 0x20001
	s_and_b32 s7, s7, 2
	s_bfe_u32 s3, s11, 0x50003
	s_lshl_b32 s6, s23, 2
	s_add_i32 s7, s7, s0
	s_add_i32 s20, s7, s6
	s_lshl_b32 s6, s3, 1
	s_ashr_i32 s22, s11, 8
	s_add_i32 s7, s6, -2
	s_cmp_gt_u32 s3, 1
	s_cselect_b32 s16, s7, 0
	s_add_i32 s6, s6, 4
	s_cmp_lt_u32 s3, 30
	s_cselect_b32 s25, s6, 64
	v_lshl_or_b32 v2, s3, 7, v173
	s_lshl_b32 s24, s22, 12
	v_or_b32_e32 v162, s24, v2
	s_lshl_b32 s6, s20, 6
	v_mov_b64_e32 v[2:3], s[80:81]
	v_mad_i64_i32 v[2:3], s[26:27], v162, s60, v[2:3]
	s_ashr_i32 s7, s6, 31
	v_lshl_add_u64 v[2:3], s[6:7], 1, v[2:3]
	v_lshlrev_b32_e32 v164, 1, v156
	v_mov_b32_e32 v165, v185
	s_ashr_i32 s21, s20, 31
	s_sub_i32 s17, s25, s16
	v_lshl_add_u64 v[2:3], v[2:3], 0, v[164:165]
	s_lshl_b64 s[20:21], s[20:21], 2
	global_load_dwordx4 v[132:135], v[2:3], off nt
	global_load_dwordx4 v[136:139], v[2:3], off offset:32 nt
	global_load_dwordx4 v[140:143], v[2:3], off offset:64 nt
	global_load_dwordx4 v[144:147], v[2:3], off offset:96 nt
	s_waitcnt lgkmcnt(0)
	s_add_u32 s20, s4, s20
	s_addc_u32 s21, s5, s21
	global_load_dword v4, v185, s[20:21]
	s_sub_i32 s3, 64, s17
	s_cmp_gt_i32 s17, 0
	s_cselect_b32 s27, s16, s3
	s_cmp_gt_i32 s27, 63
	s_mov_b64 s[20:21], -1
	s_cbranch_scc0 .LBB0_452
	s_and_b32 s3, s11, 0xffffff00
	s_lshl_b32 s78, s27, 6
	s_add_i32 s3, s3, s78
	s_add_i32 s26, s3, 0x3000
	s_mov_b64 s[20:21], 0

.LBB0_484:
	s_lshl_b32 s3, s5, 7
	s_and_b32 s23, s3, 0x380
	v_ashrrev_i32_e32 v207, 31, v206
	s_ashr_i32 s5, s4, 31
	s_add_i32 s24, s23, s11
	v_lshlrev_b64 v[4:5], 12, v[206:207]
	s_lshl_b64 s[4:5], s[4:5], 10
	v_lshl_add_u64 v[4:5], s[80:81], 0, v[4:5]
	s_ashr_i32 s25, s24, 31
	s_or_b32 s3, s4, s23
	v_lshl_add_u64 v[4:5], s[24:25], 1, v[4:5]
	v_lshlrev_b32_e32 v184, 1, v192
	s_mul_i32 s24, s3, 0x2200
	s_mul_hi_u32 s3, s3, 0x2200
	s_mul_i32 s4, s5, 0x2200
	s_or_b32 s17, s10, 4
	v_lshl_add_u64 v[4:5], v[4:5], 0, v[184:185]
	s_add_i32 s3, s3, s4
	s_lshl_b32 s4, s23, 1
	global_load_dwordx4 v[160:163], v[4:5], off nt
	global_load_dwordx4 v[156:159], v[4:5], off offset:32 nt
	global_load_dwordx4 v[152:155], v[4:5], off offset:64 nt
	global_load_dwordx4 v[148:151], v[4:5], off offset:96 nt
	s_add_u32 s4, s28, s4
	v_add_u32_e32 v4, v2, v217
	s_addc_u32 s5, s29, 0
	v_readlane_b32 s36, v241, 45
	v_ashrrev_i32_e32 v5, 31, v4
	v_add_u32_e32 v2, v2, v218
	v_readlane_b32 s37, v241, 46
	s_add_u32 s24, s36, s24
	v_lshlrev_b64 v[4:5], 12, v[4:5]
	v_ashrrev_i32_e32 v3, 31, v2
	s_addc_u32 s25, s37, s3
	v_lshl_add_u64 v[4:5], s[4:5], 0, v[4:5]
	v_lshlrev_b64 v[2:3], 12, v[2:3]
	s_lshl_b32 s3, s26, 1
	v_lshl_add_u64 v[4:5], v[4:5], 0, v[200:201]
	v_lshl_add_u64 v[2:3], s[4:5], 0, v[2:3]
	s_add_u32 s26, s24, s3
	global_load_dwordx4 v[4:7], v[4:5], off
	v_lshl_add_u64 v[2:3], v[2:3], 0, v[202:203]
	s_addc_u32 s27, s25, 0
	v_mov_b32_e32 v205, v185
	global_load_dwordx4 v[8:11], v[2:3], off
	v_lshl_add_u64 v[2:3], s[26:27], 0, v[204:205]
	v_lshl_add_u64 v[12:13], v[2:3], 0, v[196:197]
	global_load_dwordx4 v[12:15], v[12:13], off
	v_lshl_add_u64 v[2:3], v[2:3], 0, v[198:199]
	global_load_dwordx4 v[16:19], v[2:3], off
	s_or_b32 s3, s16, 64
	s_add_i32 s34, s31, 0x4040
	s_and_b64 s[26:27], s[6:7], exec
	s_cselect_b32 s3, s3, s34
	v_add_u32_e32 v2, s3, v217
	v_ashrrev_i32_e32 v3, 31, v2
	v_add_u32_e32 v20, v193, v231
	v_lshlrev_b64 v[2:3], 12, v[2:3]
	v_add_u32_e32 v237, 0x8800, v20
	v_lshl_add_u64 v[2:3], s[4:5], 0, v[2:3]
	v_lshl_add_u64 v[2:3], v[2:3], 0, v[200:201]
	v_add_u32_e32 v21, v193, v232
	v_add_u32_e32 v236, 0x8800, v21
	v_lshl_add_u64 v[208:209], s[24:25], 0, v[204:205]
	v_readlane_b32 s36, v242, 63
	v_readlane_b32 s37, v241, 0
	v_readlane_b32 s38, v241, 1
	v_readlane_b32 s39, v241, 2
	v_readlane_b32 s40, v241, 3
	v_readlane_b32 s41, v241, 4
	v_readlane_b32 s42, v241, 5
	v_readlane_b32 s43, v241, 6
	v_readlane_b32 s44, v241, 7
	v_readlane_b32 s45, v241, 8
	v_readlane_b32 s46, v241, 9
	v_readlane_b32 s47, v241, 10
	v_readlane_b32 s48, v241, 11
	v_readlane_b32 s49, v241, 12
	v_readlane_b32 s50, v241, 13
	v_readlane_b32 s51, v241, 14
	v_mov_b64_e32 v[34:35], s[36:37]
	v_mov_b64_e32 v[36:37], s[38:39]
	v_mov_b64_e32 v[38:39], s[40:41]
	v_mov_b64_e32 v[40:41], s[42:43]
	v_mov_b64_e32 v[42:43], s[44:45]
	v_mov_b64_e32 v[44:45], s[46:47]
	v_mov_b64_e32 v[46:47], s[48:49]
	v_mov_b64_e32 v[48:49], s[50:51]
	v_mov_b64_e32 v[100:101], s[70:71]
	v_mov_b64_e32 v[98:99], s[68:69]
	v_lshl_add_u64 v[210:211], s[4:5], 0, v[200:201]
	v_lshl_add_u64 v[212:213], s[4:5], 0, v[202:203]
	v_readlane_b32 s48, v241, 29
	s_waitcnt vmcnt(3)
	ds_write_b128 v234, v[4:7]
	s_waitcnt vmcnt(2)
	ds_write_b128 v235, v[8:11]
	v_add_u32_e32 v6, s3, v218
	s_lshl_b32 s3, s22, 1
	v_ashrrev_i32_e32 v7, 31, v6
	s_add_u32 s26, s24, s3
	v_lshlrev_b64 v[6:7], 12, v[6:7]
	s_addc_u32 s27, s25, 0
	s_waitcnt vmcnt(1)
	ds_write2_b64 v237, v[12:13], v[14:15] offset1:2
	v_lshl_add_u64 v[6:7], s[4:5], 0, v[6:7]
	v_lshl_add_u64 v[14:15], s[26:27], 0, v[204:205]
	global_load_dwordx4 v[2:5], v[2:3], off
	v_lshl_add_u64 v[6:7], v[6:7], 0, v[202:203]
	v_lshl_add_u64 v[10:11], v[14:15], 0, v[196:197]
	global_load_dwordx4 v[6:9], v[6:7], off
	v_lshl_add_u64 v[14:15], v[14:15], 0, v[198:199]
	global_load_dwordx4 v[10:13], v[10:11], off
	s_waitcnt vmcnt(3)
	ds_write2_b64 v236, v[16:17], v[18:19] offset1:2
	global_load_dwordx4 v[14:17], v[14:15], off
	s_add_i32 s22, s31, 0x3000
	s_sub_i32 s3, 0x42, s10
	s_and_b64 s[6:7], s[6:7], exec
	s_cselect_b32 s3, 2, s3
	s_lshl_b32 s7, s3, 6
	s_or_b32 s6, s16, 0x80
	s_add_i32 s24, s22, s7
	s_waitcnt lgkmcnt(0)
	s_barrier
	s_cmp_lt_u32 s3, 64
	s_cselect_b32 s6, s6, s24
	s_cselect_b32 s3, 0x80, s7
	s_lshl_b32 s78, s3, 1
	s_waitcnt vmcnt(3)
	ds_write_b128 v234, v[2:5] offset:17408
	s_waitcnt vmcnt(2)
	ds_write_b128 v235, v[6:9] offset:17408
	v_add_u32_e32 v2, 0xd000, v20
	s_waitcnt vmcnt(1)
	ds_write2_b64 v2, v[10:11], v[12:13] offset1:2
	v_add_u32_e32 v2, 0xd000, v21
	s_waitcnt vmcnt(0)
	ds_write2_b64 v2, v[14:15], v[16:17] offset1:2
	v_add_u32_e32 v2, s6, v217
	v_ashrrev_i32_e32 v3, 31, v2
	v_lshlrev_b64 v[2:3], 12, v[2:3]
	v_lshl_add_u64 v[2:3], s[4:5], 0, v[2:3]
	v_lshl_add_u64 v[2:3], v[2:3], 0, v[200:201]
	global_load_dwordx4 v[164:167], v[2:3], off
	v_add_u32_e32 v2, s6, v218
	v_ashrrev_i32_e32 v3, 31, v2
	v_lshlrev_b64 v[2:3], 12, v[2:3]
	v_lshl_add_u64 v[2:3], s[4:5], 0, v[2:3]
	v_lshl_add_u64 v[2:3], v[2:3], 0, v[202:203]
	global_load_dwordx4 v[168:171], v[2:3], off
	v_lshl_add_u64 v[2:3], v[208:209], 0, s[78:79]
	v_lshl_add_u64 v[4:5], v[2:3], 0, v[196:197]
	v_lshl_add_u64 v[2:3], v[2:3], 0, v[198:199]
	global_load_dwordx4 v[176:179], v[4:5], off
	global_load_dwordx4 v[172:175], v[2:3], off
	ds_read_b128 v[50:53], v214 offset:8704
	ds_read_b128 v[18:21], v214
	ds_read_b128 v[54:57], v214 offset:32
	s_waitcnt lgkmcnt(1)
	v_mfma_f32_32x32x16_bf16 v[2:17], v[18:21], v[160:163], v[34:49]
	s_mov_b32 s5, 0
	s_sub_i32 s6, 0, s10
	v_mfma_f32_32x32x16_bf16 v[18:33], v[50:53], v[160:163], v[34:49]
	s_nop 6
	ds_read_b128 v[34:37], v214 offset:8736
	s_waitcnt lgkmcnt(1)
	v_mfma_f32_32x32x16_bf16 v[2:17], v[54:57], v[156:159], v[2:17]
	s_waitcnt lgkmcnt(0)
	v_mfma_f32_32x32x16_bf16 v[18:33], v[34:37], v[156:159], v[18:33]
	ds_read_b128 v[34:37], v214 offset:64
	ds_read_b128 v[38:41], v214 offset:8768
	s_waitcnt lgkmcnt(1)
	v_mfma_f32_32x32x16_bf16 v[2:17], v[34:37], v[152:155], v[2:17]
	s_waitcnt lgkmcnt(0)
	v_mfma_f32_32x32x16_bf16 v[18:33], v[38:41], v[152:155], v[18:33]
	ds_read_b128 v[34:37], v214 offset:96
	ds_read_b128 v[38:41], v214 offset:8800
	s_waitcnt lgkmcnt(1)
	v_mfma_f32_32x32x16_bf16 v[2:17], v[34:37], v[148:151], v[2:17]
	s_waitcnt lgkmcnt(0)
	v_mfma_f32_32x32x16_bf16 v[18:33], v[38:41], v[148:151], v[18:33]
	s_nop 9
	v_max_f32_e32 v34, v3, v3
	v_max_f32_e32 v35, v2, v2
	v_max_f32_e32 v34, v35, v34
	v_max3_f32 v35, v5, v6, v7
	v_max3_f32 v34, v34, v4, v8
	v_max3_f32 v35, v35, v10, v11
	v_max3_f32 v34, v34, v9, v12
	v_max3_f32 v36, v18, v19, v20
	v_max3_f32 v37, v21, v22, v23
	v_max3_f32 v36, v36, v24, v25
	v_max3_f32 v37, v37, v26, v27
	v_max3_f32 v35, v35, v14, v15
	v_max3_f32 v36, v36, v28, v29
	v_max3_f32 v34, v34, v13, v16
	v_max3_f32 v37, v37, v30, v31
	v_max3_f32 v36, v36, v32, v33
	v_max3_f32 v34, v34, v17, v35
	v_max3_f32 v34, v34, v36, v37
	ds_bpermute_b32 v35, v67, v34
	s_waitcnt lgkmcnt(0)
	v_max_f32_e32 v35, v35, v35
	v_max_f32_e32 v205, v34, v35
	v_sub_f32_e32 v2, v2, v205
	v_sub_f32_e32 v3, v3, v205
	v_sub_f32_e32 v4, v4, v205
	v_sub_f32_e32 v5, v5, v205
	v_exp_f32_e32 v2, v2
	v_exp_f32_e32 v3, v3
	v_exp_f32_e32 v4, v4
	v_exp_f32_e32 v5, v5
	v_sub_f32_e32 v6, v6, v205
	v_sub_f32_e32 v7, v7, v205
	v_sub_f32_e32 v8, v8, v205
	v_sub_f32_e32 v9, v9, v205
	v_exp_f32_e32 v6, v6
	v_exp_f32_e32 v7, v7
	v_exp_f32_e32 v8, v8
	v_exp_f32_e32 v9, v9
	v_cvt_pk_bf16_f32 v68, v2, v3
	v_cvt_pk_bf16_f32 v69, v4, v5
	ds_read_b128 v[2:5], v215 offset:34816
	ds_read_b128 v[72:75], v215 offset:34848
	v_cvt_pk_bf16_f32 v70, v6, v7
	v_cvt_pk_bf16_f32 v71, v8, v9
	v_sub_f32_e32 v10, v10, v205
	v_sub_f32_e32 v11, v11, v205
	s_waitcnt lgkmcnt(1)
	v_mfma_f32_32x32x16_bf16 v[50:65], v[2:5], v[68:71], 0
	ds_read_b128 v[2:5], v215 offset:39424
	v_sub_f32_e32 v12, v12, v205
	v_sub_f32_e32 v13, v13, v205
	v_sub_f32_e32 v14, v14, v205
	v_sub_f32_e32 v15, v15, v205
	v_sub_f32_e32 v16, v16, v205
	v_sub_f32_e32 v17, v17, v205
	v_exp_f32_e32 v10, v10
	v_exp_f32_e32 v11, v11
	v_exp_f32_e32 v12, v12
	v_exp_f32_e32 v13, v13
	v_exp_f32_e32 v14, v14
	v_exp_f32_e32 v15, v15
	v_exp_f32_e32 v16, v16
	v_exp_f32_e32 v17, v17
	v_cvt_pk_bf16_f32 v94, v10, v11
	v_cvt_pk_bf16_f32 v95, v12, v13
	v_cvt_pk_bf16_f32 v96, v14, v15
	v_cvt_pk_bf16_f32 v97, v16, v17
	v_sub_f32_e32 v18, v18, v205
	v_sub_f32_e32 v19, v19, v205
	s_waitcnt lgkmcnt(1)
	v_mfma_f32_32x32x16_bf16 v[50:65], v[72:75], v[94:97], v[50:65]
	ds_read_b128 v[72:75], v215 offset:39456
	v_sub_f32_e32 v20, v20, v205
	v_sub_f32_e32 v21, v21, v205
	v_sub_f32_e32 v22, v22, v205
	v_sub_f32_e32 v23, v23, v205
	v_sub_f32_e32 v24, v24, v205
	v_sub_f32_e32 v25, v25, v205
	s_waitcnt lgkmcnt(1)
	v_mfma_f32_32x32x16_bf16 v[34:49], v[2:5], v[68:71], 0
	ds_read_b128 v[2:5], v215 offset:44032
	v_sub_f32_e32 v26, v26, v205
	v_sub_f32_e32 v27, v27, v205
	v_sub_f32_e32 v28, v28, v205
	v_sub_f32_e32 v29, v29, v205
	v_sub_f32_e32 v30, v30, v205
	v_sub_f32_e32 v31, v31, v205
	v_sub_f32_e32 v32, v32, v205
	v_sub_f32_e32 v33, v33, v205
	v_exp_f32_e32 v18, v18
	v_exp_f32_e32 v19, v19
	v_exp_f32_e32 v20, v20
	v_exp_f32_e32 v21, v21
	v_exp_f32_e32 v22, v22
	v_exp_f32_e32 v23, v23
	v_exp_f32_e32 v24, v24
	v_exp_f32_e32 v25, v25
	v_exp_f32_e32 v26, v26
	v_exp_f32_e32 v27, v27
	v_exp_f32_e32 v28, v28
	v_exp_f32_e32 v29, v29
	v_exp_f32_e32 v30, v30
	v_exp_f32_e32 v31, v31
	v_exp_f32_e32 v32, v32
	v_exp_f32_e32 v33, v33
	s_waitcnt lgkmcnt(1)
	v_mfma_f32_32x32x16_bf16 v[34:49], v[72:75], v[94:97], v[34:49]
	ds_read_b128 v[72:75], v215 offset:44064
	v_cvt_pk_bf16_f32 v90, v18, v19
	v_cvt_pk_bf16_f32 v91, v20, v21
	v_cvt_pk_bf16_f32 v92, v22, v23
	v_cvt_pk_bf16_f32 v93, v24, v25
	v_cvt_pk_bf16_f32 v86, v26, v27
	v_cvt_pk_bf16_f32 v87, v28, v29
	v_cvt_pk_bf16_f32 v88, v30, v31
	v_cvt_pk_bf16_f32 v89, v32, v33
	s_waitcnt lgkmcnt(1)
	v_mfma_f32_32x32x16_bf16 v[18:33], v[2:5], v[68:71], 0
	ds_read_b128 v[2:5], v215 offset:48640
	v_xor_b32_e32 v84, 0x80000000, v205
	v_mov_b32_e32 v85, v84
	s_waitcnt lgkmcnt(1)
	v_mfma_f32_32x32x16_bf16 v[18:33], v[72:75], v[94:97], v[18:33]
	ds_read_b128 v[72:75], v215 offset:48672
	s_waitcnt lgkmcnt(1)
	v_mfma_f32_32x32x16_bf16 v[2:17], v[2:5], v[68:71], 0
	s_waitcnt lgkmcnt(0)
	v_mfma_f32_32x32x16_bf16 v[2:17], v[72:75], v[94:97], v[2:17]
	ds_read_b128 v[72:75], v215 offset:34880
	s_waitcnt lgkmcnt(0)
	v_mfma_f32_32x32x16_bf16 v[50:65], v[72:75], v[90:93], v[50:65]
	ds_read_b128 v[72:75], v215 offset:39488
	s_waitcnt lgkmcnt(0)
	v_mfma_f32_32x32x16_bf16 v[34:49], v[72:75], v[90:93], v[34:49]
	ds_read_b128 v[72:75], v215 offset:44096
	s_waitcnt lgkmcnt(0)
	v_mfma_f32_32x32x16_bf16 v[18:33], v[72:75], v[90:93], v[18:33]
	ds_read_b128 v[72:75], v215 offset:48704
	s_waitcnt lgkmcnt(0)
	v_mfma_f32_32x32x16_bf16 v[2:17], v[72:75], v[90:93], v[2:17]
	ds_read_b128 v[72:75], v215 offset:34912
	s_waitcnt lgkmcnt(0)
	v_mfma_f32_32x32x16_bf16 v[50:65], v[72:75], v[86:89], v[50:65]
	ds_read_b128 v[72:75], v215 offset:39520
	s_waitcnt lgkmcnt(0)
	v_mfma_f32_32x32x16_bf16 v[34:49], v[72:75], v[86:89], v[34:49]
	ds_read_b128 v[72:75], v215 offset:44128
	s_waitcnt lgkmcnt(0)
	v_mfma_f32_32x32x16_bf16 v[18:33], v[72:75], v[86:89], v[18:33]
	ds_read_b128 v[72:75], v215 offset:48736
	s_waitcnt lgkmcnt(0)
	s_barrier
	v_mfma_f32_32x32x16_bf16 v[2:17], v[72:75], v[86:89], v[2:17]
	v_mfma_f32_32x32x16_bf16 v[68:83], v[98:101], v[68:71], 0
	v_mfma_f32_32x32x16_bf16 v[68:83], v[98:101], v[94:97], v[68:83]
	v_mov_b32_e32 v94, v84
	v_mov_b32_e32 v95, v84
	v_mov_b32_e32 v96, v84
	v_mov_b32_e32 v97, v84
	v_mfma_f32_32x32x16_bf16 v[68:83], v[98:101], v[90:93], v[68:83]
	v_mov_b32_e32 v90, v84
	v_mov_b32_e32 v91, v84
	v_mov_b32_e32 v92, v84
	v_mov_b32_e32 v93, v84
	v_mfma_f32_32x32x16_bf16 v[68:83], v[98:101], v[86:89], v[68:83]
	v_mov_b32_e32 v86, v84
	v_mov_b32_e32 v87, v84
	v_mov_b32_e32 v88, v84
	v_mov_b32_e32 v89, v84
	v_mov_b32_e32 v98, v84
	v_mov_b32_e32 v99, v84
	s_cmp_lg_u32 s100, 0
	s_cbranch_scc1 .Lattn_af_loop

.LBB0_511:
	v_cndmask_b32_e64 v26, 0, 1, s[0:1]
	s_andn2_b64 vcc, exec, s[4:5]
	v_cmp_ne_u32_e64 s[38:39], 1, v26
	s_cbranch_vccnz .LBB0_517
	v_lshl_add_u64 v[102:103], s[78:79], 2, v[130:131]
	v_add_co_u32_e32 v14, vcc, 0x400000, v102
	s_mov_b64 s[28:29], 0x400800
	s_nop 0
	v_addc_co_u32_e32 v15, vcc, 0, v103, vcc
	global_load_dwordx4 v[24:27], v[102:103], off nt
	global_load_dwordx4 v[88:91], v[14:15], off nt
	v_add_co_u32_e32 v14, vcc, 0x800000, v102
	v_lshl_add_u64 v[104:105], v[102:103], 0, s[28:29]
	s_nop 0
	v_addc_co_u32_e32 v15, vcc, 0, v103, vcc
	v_add_co_u32_e32 v16, vcc, 0xc00000, v102
	s_mov_b64 s[28:29], 0x800800
	s_nop 0
	v_addc_co_u32_e32 v17, vcc, 0, v103, vcc
	global_load_dwordx4 v[92:95], v[14:15], off nt
	global_load_dwordx4 v[96:99], v[16:17], off nt
	v_lshl_add_u64 v[106:107], v[102:103], 0, s[28:29]
	s_mov_b64 s[28:29], 0xc00800
	s_mov_b64 s[4:5], -1
	s_and_b64 vcc, exec, s[38:39]
	v_lshl_add_u64 v[100:101], v[102:103], 0, s[28:29]
	s_waitcnt vmcnt(0)
	v_pk_add_f32 v[108:109], v[30:31], v[24:25]
	s_cbranch_vccnz .LBB0_514
	v_add_co_u32_e32 v126, vcc, 0x1000000, v102
	v_lshl_add_u64 v[14:15], v[102:103], 0, s[66:67]
	s_nop 0
	v_addc_co_u32_e32 v127, vcc, 0, v103, vcc
	v_add_co_u32_e32 v172, vcc, 0x1400000, v102
	global_load_dwordx4 v[18:21], v[126:127], off nt
	s_nop 0
	global_load_dwordx4 v[14:17], v[14:15], off offset:16 nt
	v_addc_co_u32_e32 v173, vcc, 0, v103, vcc
	v_add_co_u32_e32 v28, vcc, s35, v102
	global_load_dwordx4 v[84:87], v[172:173], off nt
	global_load_dwordx4 v[22:25], v[102:103], off offset:16 nt
	v_addc_co_u32_e32 v29, vcc, 0, v103, vcc
	v_add_co_u32_e32 v176, vcc, 0x1800000, v102
	global_load_dwordx4 v[110:113], v[28:29], off offset:16 nt
	s_nop 0
	v_addc_co_u32_e32 v177, vcc, 0, v103, vcc
	v_add_co_u32_e32 v164, vcc, s72, v102
	global_load_dwordx4 v[114:117], v[176:177], off nt
	s_nop 0
	v_addc_co_u32_e32 v165, vcc, 0, v103, vcc
	v_add_co_u32_e32 v168, vcc, s73, v102
	global_load_dwordx4 v[118:121], v[164:165], off offset:16 nt
	s_nop 0
	v_addc_co_u32_e32 v169, vcc, 0, v103, vcc
	global_load_dwordx4 v[122:125], v[168:169], off offset:16 nt
	v_add_co_u32_e32 v166, vcc, 0x1c00000, v102
	v_lshl_add_u64 v[30:31], v[102:103], 0, s[80:81]
	s_nop 0
	v_addc_co_u32_e32 v167, vcc, 0, v103, vcc
	global_load_dwordx4 v[134:137], v[166:167], off nt
	global_load_dwordx4 v[138:141], v[30:31], off offset:16 nt
	v_lshl_add_u64 v[30:31], v[102:103], 0, s[74:75]
	global_load_dwordx4 v[148:151], v[30:31], off offset:16 nt
	v_lshl_add_u64 v[30:31], v[102:103], 0, s[84:85]
	global_load_dwordx4 v[152:155], v[30:31], off offset:16 nt
	global_load_dwordx4 v[156:159], v[102:103], off offset:2048 nt
	global_load_dwordx4 v[160:163], v[28:29], off offset:2048 nt
	v_pk_add_f32 v[28:29], v[32:33], v[26:27]
	v_pk_add_f32 v[30:31], v[88:89], v[108:109]
	v_pk_add_f32 v[170:171], v[90:91], v[28:29]
	v_pk_add_f32 v[174:175], v[92:93], v[30:31]
	v_pk_add_f32 v[170:171], v[94:95], v[170:171]
	global_load_dwordx4 v[28:31], v[102:103], off offset:2064 nt
	v_pk_add_f32 v[174:175], v[96:97], v[174:175]
	s_mov_b64 s[4:5], 0x1000800
	s_waitcnt vmcnt(14)
	v_pk_add_f32 v[18:19], v[174:175], v[18:19]
	s_waitcnt vmcnt(12)
	v_pk_add_f32 v[18:19], v[84:85], v[18:19]
	s_waitcnt vmcnt(11)
	v_pk_add_f32 v[178:179], v[36:37], v[24:25]
	v_pk_add_f32 v[190:191], v[34:35], v[22:23]
	global_load_dwordx4 v[22:25], v[166:167], off offset:2048 nt
	s_waitcnt vmcnt(11)
	v_pk_add_f32 v[178:179], v[112:113], v[178:179]
	v_pk_add_f32 v[190:191], v[110:111], v[190:191]
	global_load_dwordx4 v[110:113], v[164:165], off offset:2048 nt
	s_waitcnt vmcnt(11)
	v_pk_add_f32 v[18:19], v[114:115], v[18:19]
	global_load_dwordx4 v[164:167], v[126:127], off offset:2048 nt
	v_pk_add_f32 v[126:127], v[98:99], v[170:171]
	global_load_dwordx4 v[168:171], v[168:169], off offset:2048 nt
	s_nop 0
	global_load_dwordx4 v[172:175], v[172:173], off offset:2048 nt
	v_pk_add_f32 v[20:21], v[126:127], v[20:21]
	s_waitcnt vmcnt(13)
	v_pk_add_f32 v[126:127], v[120:121], v[178:179]
	v_pk_add_f32 v[178:179], v[118:119], v[190:191]
	v_pk_add_f32 v[20:21], v[86:87], v[20:21]
	s_waitcnt vmcnt(12)
	v_pk_add_f32 v[84:85], v[124:125], v[126:127]
	v_pk_add_f32 v[86:87], v[122:123], v[178:179]
	v_pk_add_f32 v[20:21], v[116:117], v[20:21]
	v_pk_add_f32 v[84:85], v[16:17], v[84:85]
	v_pk_add_f32 v[86:87], v[14:15], v[86:87]
	global_load_dwordx4 v[118:121], v[176:177], off offset:2048 nt
	s_waitcnt vmcnt(12)
	v_pk_add_f32 v[16:17], v[136:137], v[20:21]
	v_pk_add_f32 v[14:15], v[134:135], v[18:19]
	s_waitcnt vmcnt(11)
	v_pk_add_f32 v[18:19], v[140:141], v[84:85]
	v_pk_add_f32 v[20:21], v[138:139], v[86:87]
	s_waitcnt vmcnt(10)
	v_pk_add_f32 v[18:19], v[150:151], v[18:19]
	v_pk_add_f32 v[84:85], v[148:149], v[20:21]
	s_waitcnt vmcnt(9)
	v_pk_add_f32 v[20:21], v[154:155], v[18:19]
	v_pk_add_f32 v[18:19], v[152:153], v[84:85]
	global_load_dwordx4 v[84:87], v[104:105], off offset:16 nt
	global_load_dwordx4 v[114:117], v[106:107], off offset:16 nt
	global_load_dwordx4 v[122:125], v[100:101], off offset:16 nt
	v_lshl_add_u64 v[126:127], v[102:103], 0, s[4:5]
	s_mov_b64 s[4:5], 0x1400800
	global_load_dwordx4 v[134:137], v[126:127], off offset:16 nt
	v_lshl_add_u64 v[126:127], v[102:103], 0, s[4:5]
	s_mov_b64 s[4:5], 0x1800800
	v_lshl_add_u64 v[148:149], v[102:103], 0, s[4:5]
	s_mov_b64 s[4:5], 0x1c00800
	global_load_dwordx4 v[138:141], v[126:127], off offset:16 nt
	s_nop 0
	global_load_dwordx4 v[148:151], v[148:149], off offset:16 nt
	s_waitcnt vmcnt(14)
	v_pk_add_f32 v[152:153], v[38:39], v[156:157]
	v_lshl_add_u64 v[154:155], v[102:103], 0, s[4:5]
	s_waitcnt vmcnt(13)
	v_pk_add_f32 v[156:157], v[160:161], v[152:153]
	global_load_dwordx4 v[152:155], v[154:155], off offset:16 nt
	v_pk_add_f32 v[126:127], v[40:41], v[158:159]
	s_waitcnt vmcnt(13)
	v_pk_add_f32 v[30:31], v[82:83], v[30:31]
	v_pk_add_f32 v[28:29], v[80:81], v[28:29]
	v_pk_add_f32 v[126:127], v[162:163], v[126:127]
	s_mov_b64 s[4:5], 0
	s_waitcnt vmcnt(11)
	v_pk_add_f32 v[112:113], v[112:113], v[126:127]
	v_pk_add_f32 v[110:111], v[110:111], v[156:157]
	s_waitcnt vmcnt(9)
	v_pk_add_f32 v[112:113], v[170:171], v[112:113]
	v_pk_add_f32 v[110:111], v[168:169], v[110:111]
	v_pk_add_f32 v[112:113], v[166:167], v[112:113]
	v_pk_add_f32 v[110:111], v[164:165], v[110:111]
	s_waitcnt vmcnt(8)
	v_pk_add_f32 v[112:113], v[174:175], v[112:113]
	v_pk_add_f32 v[110:111], v[172:173], v[110:111]
	s_waitcnt vmcnt(7)
	v_pk_add_f32 v[112:113], v[120:121], v[112:113]
	v_pk_add_f32 v[110:111], v[118:119], v[110:111]
	v_pk_add_f32 v[24:25], v[24:25], v[112:113]
	v_pk_add_f32 v[22:23], v[22:23], v[110:111]
	s_waitcnt vmcnt(6)
	v_pk_add_f32 v[30:31], v[86:87], v[30:31]
	v_pk_add_f32 v[28:29], v[84:85], v[28:29]
	s_waitcnt vmcnt(5)
	v_pk_add_f32 v[30:31], v[116:117], v[30:31]
	v_pk_add_f32 v[28:29], v[114:115], v[28:29]
	s_waitcnt vmcnt(4)
	v_pk_add_f32 v[30:31], v[124:125], v[30:31]
	v_pk_add_f32 v[28:29], v[122:123], v[28:29]
	s_waitcnt vmcnt(3)
	v_pk_add_f32 v[30:31], v[136:137], v[30:31]
	v_pk_add_f32 v[28:29], v[134:135], v[28:29]
	s_waitcnt vmcnt(2)
	v_pk_add_f32 v[30:31], v[140:141], v[30:31]
	v_pk_add_f32 v[28:29], v[138:139], v[28:29]
	s_waitcnt vmcnt(1)
	v_pk_add_f32 v[30:31], v[150:151], v[30:31]
	v_pk_add_f32 v[28:29], v[148:149], v[28:29]
	s_waitcnt vmcnt(0)
	v_pk_add_f32 v[86:87], v[154:155], v[30:31]
	v_pk_add_f32 v[84:85], v[152:153], v[28:29]
.LBB0_514:
	s_andn2_b64 vcc, exec, s[4:5]
	s_cbranch_vccnz .LBB0_516
	v_pk_add_f32 v[14:15], v[32:33], v[26:27]
	v_add_co_u32_e32 v84, vcc, s35, v102
	v_pk_add_f32 v[14:15], v[90:91], v[14:15]
	v_pk_add_f32 v[16:17], v[88:89], v[108:109]
	v_addc_co_u32_e32 v85, vcc, 0, v103, vcc
	v_pk_add_f32 v[14:15], v[94:95], v[14:15]
	v_pk_add_f32 v[18:19], v[92:93], v[16:17]
	v_add_co_u32_e32 v86, vcc, s72, v102
	v_pk_add_f32 v[16:17], v[98:99], v[14:15]
	v_pk_add_f32 v[14:15], v[96:97], v[18:19]
	global_load_dwordx4 v[18:21], v[102:103], off offset:16 nt
	v_addc_co_u32_e32 v87, vcc, 0, v103, vcc
	global_load_dwordx4 v[22:25], v[84:85], off offset:16 nt
	global_load_dwordx4 v[26:29], v[86:87], off offset:16 nt
	v_add_co_u32_e32 v92, vcc, s73, v102
	s_nop 1
	v_addc_co_u32_e32 v93, vcc, 0, v103, vcc
	global_load_dwordx4 v[30:33], v[92:93], off offset:16 nt
	s_waitcnt vmcnt(3)
	v_pk_add_f32 v[20:21], v[36:37], v[20:21]
	v_pk_add_f32 v[18:19], v[34:35], v[18:19]
	s_waitcnt vmcnt(2)
	v_pk_add_f32 v[20:21], v[24:25], v[20:21]
	v_pk_add_f32 v[18:19], v[22:23], v[18:19]
	s_waitcnt vmcnt(1)
	v_pk_add_f32 v[20:21], v[28:29], v[20:21]
	v_pk_add_f32 v[18:19], v[26:27], v[18:19]
	s_waitcnt vmcnt(0)
	v_pk_add_f32 v[20:21], v[32:33], v[20:21]
	v_pk_add_f32 v[18:19], v[30:31], v[18:19]
	global_load_dwordx4 v[26:29], v[102:103], off offset:2064 nt
	global_load_dwordx4 v[22:25], v[102:103], off offset:2048 nt
	global_load_dwordx4 v[30:33], v[84:85], off offset:2048 nt
	global_load_dwordx4 v[34:37], v[104:105], off offset:16 nt
	s_nop 0
	global_load_dwordx4 v[84:87], v[86:87], off offset:2048 nt
	s_nop 0
	global_load_dwordx4 v[88:91], v[106:107], off offset:16 nt
	s_nop 0
	global_load_dwordx4 v[92:95], v[92:93], off offset:2048 nt
	s_nop 0
	global_load_dwordx4 v[96:99], v[100:101], off offset:16 nt
	s_waitcnt vmcnt(7)
	v_pk_add_f32 v[28:29], v[82:83], v[28:29]
	s_waitcnt vmcnt(6)
	v_pk_add_f32 v[24:25], v[40:41], v[24:25]
	v_pk_add_f32 v[22:23], v[38:39], v[22:23]
	v_pk_add_f32 v[26:27], v[80:81], v[26:27]
	s_waitcnt vmcnt(5)
	v_pk_add_f32 v[24:25], v[32:33], v[24:25]
	v_pk_add_f32 v[22:23], v[30:31], v[22:23]
	s_waitcnt vmcnt(4)
	v_pk_add_f32 v[28:29], v[36:37], v[28:29]
	v_pk_add_f32 v[26:27], v[34:35], v[26:27]
	s_waitcnt vmcnt(3)
	v_pk_add_f32 v[24:25], v[86:87], v[24:25]
	v_pk_add_f32 v[22:23], v[84:85], v[22:23]
	s_waitcnt vmcnt(2)
	v_pk_add_f32 v[28:29], v[90:91], v[28:29]
	v_pk_add_f32 v[26:27], v[88:89], v[26:27]
	s_waitcnt vmcnt(1)
	v_pk_add_f32 v[24:25], v[94:95], v[24:25]
	v_pk_add_f32 v[22:23], v[92:93], v[22:23]
	s_waitcnt vmcnt(0)
	v_pk_add_f32 v[86:87], v[98:99], v[28:29]
	v_pk_add_f32 v[84:85], v[96:97], v[26:27]

.LBB0_519:
	s_andn2_b64 vcc, exec, s[4:5]
	s_cbranch_vccnz .LBB0_525
	s_add_i32 s4, s55, s78
	s_mov_b32 s5, s79
	v_lshl_add_u64 v[134:135], s[4:5], 2, v[130:131]
	v_add_co_u32_e32 v26, vcc, 0x400000, v134
	s_mov_b64 s[28:29], -1
	s_nop 0
	v_addc_co_u32_e32 v27, vcc, 0, v135, vcc
	global_load_dwordx4 v[36:39], v[134:135], off nt
	global_load_dwordx4 v[88:91], v[26:27], off nt
	v_add_co_u32_e32 v26, vcc, 0x800000, v134
	s_waitcnt vmcnt(0)
	v_pk_add_f32 v[2:3], v[2:3], v[36:37]
	v_addc_co_u32_e32 v27, vcc, 0, v135, vcc
	v_add_co_u32_e32 v28, vcc, 0xc00000, v134
	s_nop 1
	v_addc_co_u32_e32 v29, vcc, 0, v135, vcc
	global_load_dwordx4 v[92:95], v[26:27], off nt
	global_load_dwordx4 v[96:99], v[28:29], off nt
	s_and_b64 vcc, exec, s[38:39]
	s_mov_b64 s[38:39], 0x400800
	v_lshl_add_u64 v[136:137], v[134:135], 0, s[38:39]
	s_mov_b64 s[38:39], 0x800800
	v_lshl_add_u64 v[138:139], v[134:135], 0, s[38:39]
	s_mov_b64 s[38:39], 0xc00800
	v_lshl_add_u64 v[40:41], v[134:135], 0, s[38:39]
	s_cbranch_vccnz .LBB0_522
	v_add_co_u32_e32 v34, vcc, 0x1000000, v134
	v_lshl_add_u64 v[30:31], v[134:135], 0, s[66:67]
	s_nop 0
	v_addc_co_u32_e32 v35, vcc, 0, v135, vcc
	v_add_co_u32_e32 v36, vcc, 0x1400000, v134
	global_load_dwordx4 v[26:29], v[34:35], off nt
	s_nop 0
	global_load_dwordx4 v[30:33], v[30:31], off offset:16 nt
	v_addc_co_u32_e32 v37, vcc, 0, v135, vcc
	v_add_co_u32_e32 v124, vcc, 0x1800000, v134
	v_lshl_add_u64 v[104:105], v[134:135], 0, s[80:81]
	s_nop 0
	v_addc_co_u32_e32 v125, vcc, 0, v135, vcc
	global_load_dwordx4 v[100:103], v[36:37], off nt
	s_nop 0
	global_load_dwordx4 v[104:107], v[104:105], off offset:16 nt
	v_lshl_add_u64 v[112:113], v[134:135], 0, s[74:75]
	v_add_co_u32_e32 v140, vcc, 0x1c00000, v134
	global_load_dwordx4 v[108:111], v[124:125], off nt
	s_nop 0
	global_load_dwordx4 v[112:115], v[112:113], off offset:16 nt
	v_lshl_add_u64 v[120:121], v[134:135], 0, s[84:85]
	v_addc_co_u32_e32 v141, vcc, 0, v135, vcc
	global_load_dwordx4 v[116:119], v[140:141], off nt
	s_nop 0
	global_load_dwordx4 v[120:123], v[120:121], off offset:16 nt
	v_pk_add_f32 v[126:127], v[4:5], v[38:39]
	v_pk_add_f32 v[148:149], v[88:89], v[2:3]
	v_pk_add_f32 v[126:127], v[90:91], v[126:127]
	s_waitcnt vmcnt(9)
	v_pk_add_f32 v[148:149], v[92:93], v[148:149]
	v_pk_add_f32 v[126:127], v[94:95], v[126:127]
	s_waitcnt vmcnt(8)
	v_pk_add_f32 v[148:149], v[96:97], v[148:149]
	v_pk_add_f32 v[126:127], v[98:99], v[126:127]
	s_mov_b64 s[28:29], 0x1000800
	s_waitcnt vmcnt(7)
	v_pk_add_f32 v[28:29], v[126:127], v[28:29]
	v_add_co_u32_e32 v126, vcc, s35, v134
	v_pk_add_f32 v[26:27], v[148:149], v[26:27]
	s_nop 0
	v_addc_co_u32_e32 v127, vcc, 0, v135, vcc
	v_add_co_u32_e32 v156, vcc, s72, v134
	s_waitcnt vmcnt(5)
	v_pk_add_f32 v[28:29], v[102:103], v[28:29]
	v_pk_add_f32 v[26:27], v[100:101], v[26:27]
	global_load_dwordx4 v[100:103], v[134:135], off offset:16 nt
	v_addc_co_u32_e32 v157, vcc, 0, v135, vcc
	s_waitcnt vmcnt(4)
	v_pk_add_f32 v[28:29], v[110:111], v[28:29]
	v_pk_add_f32 v[26:27], v[108:109], v[26:27]
	global_load_dwordx4 v[108:111], v[126:127], off offset:16 nt
	v_add_co_u32_e32 v160, vcc, s73, v134
	s_waitcnt vmcnt(3)
	v_pk_add_f32 v[28:29], v[118:119], v[28:29]
	v_pk_add_f32 v[26:27], v[116:117], v[26:27]
	global_load_dwordx4 v[116:119], v[156:157], off offset:16 nt
	v_addc_co_u32_e32 v161, vcc, 0, v135, vcc
	global_load_dwordx4 v[148:151], v[160:161], off offset:16 nt
	s_waitcnt vmcnt(3)
	v_pk_add_f32 v[102:103], v[8:9], v[102:103]
	v_pk_add_f32 v[100:101], v[6:7], v[100:101]
	s_waitcnt vmcnt(2)
	v_pk_add_f32 v[102:103], v[110:111], v[102:103]
	v_pk_add_f32 v[100:101], v[108:109], v[100:101]
	s_waitcnt vmcnt(1)
	v_pk_add_f32 v[102:103], v[118:119], v[102:103]
	v_pk_add_f32 v[100:101], v[116:117], v[100:101]
	v_lshl_add_u64 v[116:117], v[134:135], 0, s[28:29]
	s_waitcnt vmcnt(0)
	v_pk_add_f32 v[102:103], v[150:151], v[102:103]
	v_pk_add_f32 v[100:101], v[148:149], v[100:101]
	v_pk_add_f32 v[32:33], v[32:33], v[102:103]
	v_pk_add_f32 v[30:31], v[30:31], v[100:101]
	v_pk_add_f32 v[32:33], v[106:107], v[32:33]
	v_pk_add_f32 v[30:31], v[104:105], v[30:31]
	v_pk_add_f32 v[32:33], v[114:115], v[32:33]
	v_pk_add_f32 v[30:31], v[112:113], v[30:31]
	global_load_dwordx4 v[100:103], v[134:135], off offset:2064 nt
	global_load_dwordx4 v[148:151], v[134:135], off offset:2048 nt
	global_load_dwordx4 v[152:155], v[126:127], off offset:2048 nt
	global_load_dwordx4 v[104:107], v[136:137], off offset:16 nt
	s_nop 0
	global_load_dwordx4 v[156:159], v[156:157], off offset:2048 nt
	s_nop 0
	global_load_dwordx4 v[108:111], v[138:139], off offset:16 nt
	s_nop 0
	global_load_dwordx4 v[160:163], v[160:161], off offset:2048 nt
	s_nop 0
	global_load_dwordx4 v[112:115], v[40:41], off offset:16 nt
	s_mov_b64 s[28:29], 0x1400800
	v_pk_add_f32 v[30:31], v[120:121], v[30:31]
	global_load_dwordx4 v[164:167], v[34:35], off offset:2048 nt
	s_nop 0
	global_load_dwordx4 v[116:119], v[116:117], off offset:16 nt
	v_lshl_add_u64 v[120:121], v[134:135], 0, s[28:29]
	s_mov_b64 s[28:29], 0x1800800
	v_pk_add_f32 v[32:33], v[122:123], v[32:33]
	global_load_dwordx4 v[34:37], v[36:37], off offset:2048 nt
	s_nop 0
	global_load_dwordx4 v[120:123], v[120:121], off offset:16 nt
	v_lshl_add_u64 v[126:127], v[134:135], 0, s[28:29]
	s_mov_b64 s[28:29], 0x1c00800
	global_load_dwordx4 v[168:171], v[124:125], off offset:2048 nt
	s_nop 0
	global_load_dwordx4 v[124:127], v[126:127], off offset:16 nt
	v_lshl_add_u64 v[176:177], v[134:135], 0, s[28:29]
	global_load_dwordx4 v[172:175], v[140:141], off offset:2048 nt
	s_nop 0
	global_load_dwordx4 v[176:179], v[176:177], off offset:16 nt
	s_mov_b64 s[28:29], 0
	s_waitcnt vmcnt(15)
	v_pk_add_f32 v[102:103], v[60:61], v[102:103]
	s_waitcnt vmcnt(14)
	v_pk_add_f32 v[140:141], v[12:13], v[150:151]
	v_pk_add_f32 v[148:149], v[10:11], v[148:149]
	v_pk_add_f32 v[100:101], v[58:59], v[100:101]
	s_waitcnt vmcnt(13)
	v_pk_add_f32 v[140:141], v[154:155], v[140:141]
	v_pk_add_f32 v[148:149], v[152:153], v[148:149]
	s_waitcnt vmcnt(12)
	v_pk_add_f32 v[102:103], v[106:107], v[102:103]
	v_pk_add_f32 v[100:101], v[104:105], v[100:101]
	s_waitcnt vmcnt(11)
	v_pk_add_f32 v[140:141], v[158:159], v[140:141]
	v_pk_add_f32 v[148:149], v[156:157], v[148:149]
	s_waitcnt vmcnt(10)
	v_pk_add_f32 v[102:103], v[110:111], v[102:103]
	v_pk_add_f32 v[100:101], v[108:109], v[100:101]
	s_waitcnt vmcnt(9)
	v_pk_add_f32 v[140:141], v[162:163], v[140:141]
	v_pk_add_f32 v[148:149], v[160:161], v[148:149]
	s_waitcnt vmcnt(8)
	v_pk_add_f32 v[102:103], v[114:115], v[102:103]
	v_pk_add_f32 v[100:101], v[112:113], v[100:101]
	s_waitcnt vmcnt(7)
	v_pk_add_f32 v[140:141], v[166:167], v[140:141]
	v_pk_add_f32 v[148:149], v[164:165], v[148:149]
	s_waitcnt vmcnt(6)
	v_pk_add_f32 v[102:103], v[118:119], v[102:103]
	v_pk_add_f32 v[100:101], v[116:117], v[100:101]
	s_waitcnt vmcnt(5)
	v_pk_add_f32 v[36:37], v[36:37], v[140:141]
	v_pk_add_f32 v[34:35], v[34:35], v[148:149]
	s_waitcnt vmcnt(4)
	v_pk_add_f32 v[102:103], v[122:123], v[102:103]
	v_pk_add_f32 v[100:101], v[120:121], v[100:101]
	s_waitcnt vmcnt(3)
	v_pk_add_f32 v[36:37], v[170:171], v[36:37]
	v_pk_add_f32 v[34:35], v[168:169], v[34:35]
	s_waitcnt vmcnt(2)
	v_pk_add_f32 v[102:103], v[126:127], v[102:103]
	v_pk_add_f32 v[100:101], v[124:125], v[100:101]
	s_waitcnt vmcnt(1)
	v_pk_add_f32 v[36:37], v[174:175], v[36:37]
	v_pk_add_f32 v[34:35], v[172:173], v[34:35]
	s_waitcnt vmcnt(0)
	v_pk_add_f32 v[102:103], v[178:179], v[102:103]
	v_pk_add_f32 v[100:101], v[176:177], v[100:101]
.LBB0_522:
	s_andn2_b64 vcc, exec, s[28:29]
	s_cbranch_vccnz .LBB0_524
	v_pk_add_f32 v[4:5], v[4:5], v[38:39]
	v_add_co_u32_e32 v38, vcc, s35, v134
	v_pk_add_f32 v[4:5], v[90:91], v[4:5]
	v_pk_add_f32 v[2:3], v[88:89], v[2:3]
	v_addc_co_u32_e32 v39, vcc, 0, v135, vcc
	s_waitcnt vmcnt(1)
	v_pk_add_f32 v[4:5], v[94:95], v[4:5]
	v_pk_add_f32 v[2:3], v[92:93], v[2:3]
	v_add_co_u32_e32 v92, vcc, s72, v134
	s_waitcnt vmcnt(0)
	v_pk_add_f32 v[28:29], v[98:99], v[4:5]
	v_pk_add_f32 v[26:27], v[96:97], v[2:3]
	global_load_dwordx4 v[2:5], v[134:135], off offset:16 nt
	v_addc_co_u32_e32 v93, vcc, 0, v135, vcc
	global_load_dwordx4 v[30:33], v[38:39], off offset:16 nt
	global_load_dwordx4 v[34:37], v[92:93], off offset:16 nt
	v_add_co_u32_e32 v100, vcc, s73, v134
	s_nop 1
	v_addc_co_u32_e32 v101, vcc, 0, v135, vcc
	global_load_dwordx4 v[88:91], v[100:101], off offset:16 nt
	s_waitcnt vmcnt(3)
	v_pk_add_f32 v[4:5], v[8:9], v[4:5]
	v_pk_add_f32 v[2:3], v[6:7], v[2:3]
	s_waitcnt vmcnt(2)
	v_pk_add_f32 v[4:5], v[32:33], v[4:5]
	v_pk_add_f32 v[2:3], v[30:31], v[2:3]
	s_waitcnt vmcnt(1)
	v_pk_add_f32 v[4:5], v[36:37], v[4:5]
	v_pk_add_f32 v[2:3], v[34:35], v[2:3]
	s_waitcnt vmcnt(0)
	v_pk_add_f32 v[32:33], v[90:91], v[4:5]
	v_pk_add_f32 v[30:31], v[88:89], v[2:3]
	global_load_dwordx4 v[2:5], v[134:135], off offset:2064 nt
	global_load_dwordx4 v[6:9], v[134:135], off offset:2048 nt
	global_load_dwordx4 v[34:37], v[38:39], off offset:2048 nt
	global_load_dwordx4 v[88:91], v[136:137], off offset:16 nt
	s_nop 0
	global_load_dwordx4 v[92:95], v[92:93], off offset:2048 nt
	s_nop 0
	global_load_dwordx4 v[96:99], v[138:139], off offset:16 nt
	s_nop 0
	global_load_dwordx4 v[100:103], v[100:101], off offset:2048 nt
	s_nop 0
	global_load_dwordx4 v[38:41], v[40:41], off offset:16 nt
	s_waitcnt vmcnt(7)
	v_pk_add_f32 v[4:5], v[60:61], v[4:5]
	s_waitcnt vmcnt(6)
	v_pk_add_f32 v[8:9], v[12:13], v[8:9]
	v_pk_add_f32 v[6:7], v[10:11], v[6:7]
	v_pk_add_f32 v[2:3], v[58:59], v[2:3]
	s_waitcnt vmcnt(5)
	v_pk_add_f32 v[8:9], v[36:37], v[8:9]
	v_pk_add_f32 v[6:7], v[34:35], v[6:7]
	s_waitcnt vmcnt(4)
	v_pk_add_f32 v[4:5], v[90:91], v[4:5]
	v_pk_add_f32 v[2:3], v[88:89], v[2:3]
	s_waitcnt vmcnt(3)
	v_pk_add_f32 v[8:9], v[94:95], v[8:9]
	v_pk_add_f32 v[6:7], v[92:93], v[6:7]
	s_waitcnt vmcnt(2)
	v_pk_add_f32 v[4:5], v[98:99], v[4:5]
	v_pk_add_f32 v[2:3], v[96:97], v[2:3]
	s_waitcnt vmcnt(1)
	v_pk_add_f32 v[36:37], v[102:103], v[8:9]
	v_pk_add_f32 v[34:35], v[100:101], v[6:7]
	s_waitcnt vmcnt(0)
	v_pk_add_f32 v[102:103], v[40:41], v[4:5]
	v_pk_add_f32 v[100:101], v[38:39], v[2:3]
